# speedup vs baseline: 1.0173x; 1.0173x over previous
; #define LAS __attribute__((address_space(3)))
; __device__ __forceinline__ void transpose_item(const float* W, const float* gk, int K, int N, bf16* WT, int kshift, LAS float* scr, int item, int lane, bool perm) {
;     const int nblk = N / 32, kb = item / nblk, nb = item % nblk, k0 = 64 * kb, n0 = 32 * nb;
; #pragma unroll 8
;     for (int i = 0; i < 32; ++i) { const int kk = 2 * i + (lane >> 5); float v = W[(size_t)(k0 + kk) * N + n0 + (lane & 31)]; if (gk) v *= gk[k0 + kk]; scr[kk * 33 + (lane & 31)] = v; }
.LBB0_21:
	v_lshl_add_u64 v[36:37], v[34:35], 0, s[26:27]
	global_load_dword v212, v[36:37], off
	v_lshl_add_u64 v[36:37], v[30:31], 0, s[26:27]
	global_load_dword v213, v[36:37], off
	v_lshl_add_u64 v[36:37], v[28:29], 0, s[26:27]
	global_load_dword v214, v[36:37], off
	v_lshl_add_u64 v[36:37], v[26:27], 0, s[26:27]
	global_load_dword v215, v[36:37], off
	v_lshl_add_u64 v[36:37], v[24:25], 0, s[26:27]
	global_load_dword v216, v[36:37], off
	v_lshl_add_u64 v[36:37], v[22:23], 0, s[26:27]
	global_load_dword v217, v[36:37], off
	v_lshl_add_u64 v[36:37], v[20:21], 0, s[26:27]
	global_load_dword v218, v[36:37], off
	v_lshl_add_u64 v[36:37], v[2:3], 0, s[26:27]
	global_load_dword v219, v[36:37], off
	s_andn2_b64 vcc, exec, s[28:29]
	s_cbranch_vccnz .Lw1t_nogain
	v_lshl_add_u64 v[36:37], v[32:33], 0, s[6:7]
	global_load_dword v220, v[36:37], off
	v_lshl_add_u64 v[36:37], v[4:5], 0, s[6:7]
	global_load_dword v221, v[36:37], off offset:8
	global_load_dword v222, v[36:37], off offset:16
	global_load_dword v223, v[36:37], off offset:24
	global_load_dword v224, v[36:37], off offset:32
	global_load_dword v225, v[36:37], off offset:40
	global_load_dword v226, v[36:37], off offset:48
	global_load_dword v227, v[36:37], off offset:56
	s_waitcnt vmcnt(0)
	v_mul_f32_e32 v212, v212, v220
	v_mul_f32_e32 v213, v213, v221
	v_mul_f32_e32 v214, v214, v222
	v_mul_f32_e32 v215, v215, v223
	v_mul_f32_e32 v216, v216, v224
	v_mul_f32_e32 v217, v217, v225
	v_mul_f32_e32 v218, v218, v226
	v_mul_f32_e32 v219, v219, v227
	s_branch .Lw1t_write

; __device__ __forceinline__ void transpose_item(const float* W, const float* gk, int K, int N, bf16* WT, int kshift, LAS float* scr, int item, int lane, bool perm) {
;     ...
;     for (int i = 0; i < 32; ++i) { const int kk = 2 * i + (lane >> 5); float v = W[(size_t)(k0 + kk) * N + n0 + (lane & 31)]; if (gk) v *= gk[k0 + kk]; scr[kk * 33 + (lane & 31)] = v; }
;     asm volatile("s_waitcnt lgkmcnt(0)" ::: "memory");
.Lw1t_write:
	ds_write_b32 v8, v212
	ds_write_b32 v8, v213 offset:264
	ds_write_b32 v8, v214 offset:528
	ds_write_b32 v8, v215 offset:792
	ds_write_b32 v8, v216 offset:1056
	ds_write_b32 v8, v217 offset:1320
	ds_write_b32 v8, v218 offset:1584
	ds_write_b32 v8, v219 offset:1848
	s_add_u32 s26, s26, 0x70000
	s_addc_u32 s27, s27, 0
	v_add_u32_e32 v8, 0x840, v8
	v_lshl_add_u64 v[4:5], v[4:5], 0, 64
	s_cmp_eq_u32 s26, 0x1c0000
	v_lshl_add_u64 v[32:33], v[32:33], 0, 64
	s_cbranch_scc0 .LBB0_21
